# attention output: lane rows exchanged with v_permlane16_swap, two 16-byte write-through stores per lane instead of four 8-byte ones
# baseline (speedup 1.0000x reference)
; __device__ __forceinline__ unsigned cvt_pk_bf16(float lo, float hi) { unsigned r; asm volatile("v_cvt_pk_bf16_f32 %0, %1, %2" : "=v"(r) : "v"(lo), "v"(hi)); return r; }
; __device__ __forceinline__ void attn_phase(const Params& p, LAS unsigned char* lds) {
;     ...
;         float q2 = 0.f;
; #pragma unroll
;         for (int nb = 0; nb < 4; ++nb) { o[nb] = o[nb] * inv; q2 += (o[nb][0] * o[nb][0] + o[nb][1] * o[nb][1]) + (o[nb][2] * o[nb][2] + o[nb][3] * o[nb][3]); }
;         q2 += __shfl_xor(q2, 16); q2 += __shfl_xor(q2, 32);
;         if (fq == 0) SSQNA[(size_t)tq * 8 + h] = q2;
;         bf16_t* op = YCAT + (size_t)tq * DM + 512 + h * 64 + 4 * fq;
; #pragma unroll
;         for (int nb = 0; nb < 4; ++nb) { u32x2 wv; wv.x = cvt_pk_bf16(o[nb][0], o[nb][1]); wv.y = cvt_pk_bf16(o[nb][2], o[nb][3]); *(u32x2*)(op + nb * 16) = wv; }
.LBB0_336:
	s_or_b64 exec, exec, s[20:21]
	v_lshlrev_b64 v[16:17], 11, v[16:17]
	v_lshl_add_u64 v[16:17], s[34:35], 0, v[16:17]
	s_lshl_b32 s16, s42, 7
	v_lshl_add_u64 v[16:17], v[16:17], 0, s[16:17]
	v_lshl_add_u64 v[16:17], v[16:17], 0, v[30:31]
	v_cvt_pk_bf16_f32 v134, v10, v11
	v_cvt_pk_bf16_f32 v135, v2, v3
	v_cvt_pk_bf16_f32 v136, v6, v7
	v_cvt_pk_bf16_f32 v137, v0, v1
	v_cvt_pk_bf16_f32 v138, v12, v13
	v_cvt_pk_bf16_f32 v139, v4, v5
	v_cvt_pk_bf16_f32 v140, v14, v15
	v_cvt_pk_bf16_f32 v141, v8, v9
	v_and_b32_e32 v142, 1, v129
	v_mul_u32_u24_e32 v142, 24, v142
	v_permlane16_swap_b32_e32 v134, v136
	v_permlane16_swap_b32_e32 v135, v137
	v_permlane16_swap_b32_e32 v138, v140
	v_permlane16_swap_b32_e32 v139, v141
	s_waitcnt lgkmcnt(0)
	v_lshl_add_u64 v[18:19], v[16:17], 0, s[6:7]
	v_mov_b32_e32 v143, 0
	v_lshl_add_u64 v[18:19], v[18:19], 0, v[142:143]
	s_mov_b64 s[20:21], 0
	global_store_dwordx4 v[18:19], v[134:137], off sc1
	global_store_dwordx4 v[18:19], v[138:141], off offset:64 sc1

; __device__ __forceinline__ void attn_phase(const Params& p, LAS unsigned char* lds) {
;     ...
;     for (;;) {
;         __syncthreads();
;         if (tid == 0) slot[0] = __hip_atomic_fetch_add(ctr, 1u, __ATOMIC_RELAXED, __HIP_MEMORY_SCOPE_AGENT);
;         __syncthreads();
;         const int item = (int)slot[0];
.LBB0_338:
	s_waitcnt vmcnt(2)
	s_barrier
	s_and_saveexec_b64 s[20:21], s[58:59]
	s_cbranch_execz .LBB0_342
	v_mov_b32_e32 v1, s33
	ds_write_b32 v1, v242
